# norm phases: first two rows of a chunk requested before the modulation vectors are staged
# baseline (speedup 1.0000x reference)
.LBB0_834:
	s_or_b64 exec, exec, s[18:19]
	v_add_u32_e32 v24, s36, v1
	v_ashrrev_i32_e32 v25, 31, v24
	v_lshlrev_b64 v[26:27], 11, v[24:25]
	v_lshl_add_u64 v[2:3], v[20:21], 0, v[26:27]
	s_waitcnt lgkmcnt(0)
	s_barrier
	s_waitcnt vmcnt(0)
	v_mov_b64_e32 v[32:33], v[210:211]
	v_mov_b64_e32 v[30:31], v[212:213]
	v_mov_b64_e32 v[36:37], v[214:215]
	v_mov_b64_e32 v[34:35], v[216:217]
	v_or_b32_e32 v2, 1, v24
	v_ashrrev_i32_e32 v3, 31, v2
	v_lshlrev_b64 v[28:29], 11, v[2:3]
	v_lshl_add_u64 v[2:3], v[20:21], 0, v[28:29]
	v_mov_b64_e32 v[38:39], v[218:219]
	v_mov_b64_e32 v[46:47], v[220:221]
	v_mov_b64_e32 v[90:91], v[222:223]
	v_mov_b64_e32 v[92:93], v[224:225]
	v_or_b32_e32 v40, 2, v24
	v_ashrrev_i32_e32 v41, 31, v40
	v_lshl_add_u64 v[94:95], v[22:23], 0, v[26:27]
	v_lshlrev_b64 v[26:27], 11, v[40:41]
	v_lshl_add_u64 v[96:97], v[20:21], 0, v[26:27]
	ds_read_b128 v[42:45], v49 offset:4096
	ds_read_b128 v[62:65], v49 offset:4096
	ds_read_b128 v[66:69], v49
	ds_read_b128 v[70:73], v49
	ds_read_b128 v[74:77], v49 offset:5120
	ds_read_b128 v[10:13], v49 offset:5120
	ds_read_b128 v[78:81], v49 offset:1024
	ds_read_b128 v[14:17], v49 offset:1024
	ds_read_b128 v[82:85], v49 offset:6144
	ds_read_b128 v[2:5], v49 offset:6144
	ds_read_b128 v[86:89], v49 offset:2048
	ds_read_b128 v[6:9], v49 offset:2048
	v_or_b32_e32 v24, 3, v24
	v_lshl_add_u64 v[26:27], v[22:23], 0, v[26:27]
	s_add_i32 s35, s35, s84
	s_cmpk_gt_i32 s35, 0x1ff
	s_waitcnt vmcnt(7)
	v_and_b32_e32 v101, 0xffff0000, v32
	s_waitcnt vmcnt(6)
	v_and_b32_e32 v100, 0xffff0000, v30
	v_lshlrev_b32_e32 v99, 16, v32
	v_lshlrev_b32_e32 v98, 16, v30
	v_lshlrev_b32_e32 v103, 16, v33
	v_and_b32_e32 v105, 0xffff0000, v33
	s_waitcnt vmcnt(5)
	v_and_b32_e32 v107, 0xffff0000, v36
	s_waitcnt vmcnt(4)
	v_and_b32_e32 v106, 0xffff0000, v34
	v_pk_mul_f32 v[32:33], v[100:101], v[100:101]
	v_lshlrev_b32_e32 v102, 16, v31
	v_and_b32_e32 v104, 0xffff0000, v31
	v_lshlrev_b32_e32 v31, 16, v36
	v_lshlrev_b32_e32 v30, 16, v34
	v_lshlrev_b32_e32 v108, 16, v35
	v_and_b32_e32 v110, 0xffff0000, v35
	v_pk_mul_f32 v[34:35], v[106:107], v[106:107]
	v_pk_fma_f32 v[32:33], v[98:99], v[98:99], v[32:33]
	v_lshlrev_b32_e32 v109, 16, v37
	v_pk_fma_f32 v[34:35], v[30:31], v[30:31], v[34:35]
	v_pk_fma_f32 v[32:33], v[102:103], v[102:103], v[32:33]
	v_and_b32_e32 v111, 0xffff0000, v37
	v_pk_fma_f32 v[34:35], v[108:109], v[108:109], v[34:35]
	v_pk_fma_f32 v[32:33], v[104:105], v[104:105], v[32:33]
	v_pk_fma_f32 v[34:35], v[110:111], v[110:111], v[34:35]
	v_add_f32_e32 v25, v32, v33
	v_add_f32_e32 v25, v25, v34
	v_add_f32_e32 v25, v25, v35
	ds_bpermute_b32 v32, v50, v25
	s_waitcnt vmcnt(2)
	v_lshlrev_b32_e32 v112, 16, v46
	v_and_b32_e32 v114, 0xffff0000, v46
	v_and_b32_e32 v115, 0xffff0000, v38
	v_lshlrev_b32_e32 v113, 16, v38
	s_waitcnt lgkmcnt(0)
	v_add_f32_e32 v25, v25, v32
	ds_bpermute_b32 v32, v51, v25
	v_lshlrev_b32_e32 v116, 16, v47
	v_and_b32_e32 v40, 0xffff0000, v47
	s_waitcnt vmcnt(1)
	v_and_b32_e32 v37, 0xffff0000, v90
	s_waitcnt vmcnt(0)
	v_and_b32_e32 v36, 0xffff0000, v92
	s_waitcnt lgkmcnt(0)
	v_add_f32_e32 v25, v25, v32
	ds_bpermute_b32 v46, v52, v25
	v_lshlrev_b32_e32 v117, 16, v39
	v_and_b32_e32 v41, 0xffff0000, v39
	v_lshlrev_b32_e32 v39, 16, v90
	v_lshlrev_b32_e32 v38, 16, v92
	s_waitcnt lgkmcnt(0)
	v_add_f32_e32 v25, v25, v46
	v_pk_mul_f32 v[46:47], v[114:115], v[114:115]
	v_lshlrev_b32_e32 v35, 16, v91
	v_and_b32_e32 v33, 0xffff0000, v91
	v_pk_mul_f32 v[90:91], v[36:37], v[36:37]
	v_pk_fma_f32 v[46:47], v[112:113], v[112:113], v[46:47]
	v_lshlrev_b32_e32 v34, 16, v93
	v_pk_fma_f32 v[90:91], v[38:39], v[38:39], v[90:91]
	v_pk_fma_f32 v[46:47], v[116:117], v[116:117], v[46:47]
	v_and_b32_e32 v32, 0xffff0000, v93
	v_pk_fma_f32 v[90:91], v[34:35], v[34:35], v[90:91]
	v_pk_fma_f32 v[46:47], v[40:41], v[40:41], v[46:47]
	v_pk_fma_f32 v[90:91], v[32:33], v[32:33], v[90:91]
	v_add_f32_e32 v46, v46, v47
	v_add_f32_e32 v46, v46, v90
	v_add_f32_e32 v46, v46, v91
	global_load_dwordx2 v[90:91], v[96:97], off
	global_load_dwordx2 v[92:93], v[96:97], off offset:512
	global_load_dwordx2 v[118:119], v[96:97], off offset:1024
	s_nop 0
	global_load_dwordx2 v[96:97], v[96:97], off offset:1536
	ds_bpermute_b32 v61, v53, v25
	ds_bpermute_b32 v47, v50, v46
	s_waitcnt lgkmcnt(1)
	v_add_f32_e32 v25, v25, v61
	ds_bpermute_b32 v61, v54, v25
	s_waitcnt lgkmcnt(1)
	v_add_f32_e32 v46, v46, v47
	ds_bpermute_b32 v47, v51, v46
	s_waitcnt lgkmcnt(1)
	v_add_f32_e32 v25, v25, v61
	ds_bpermute_b32 v61, v55, v25
	s_waitcnt lgkmcnt(0)
	v_add_f32_e32 v25, v25, v61
	v_fmamk_f32 v25, v25, 0x3a800000, v60
	v_mul_f32_e32 v61, 0x4b800000, v25
	v_cmp_gt_f32_e32 vcc, s34, v25
	s_nop 1
	v_cndmask_b32_e32 v25, v25, v61, vcc
	v_rsq_f32_e32 v25, v25
	s_nop 0
	v_mul_f32_e32 v61, 0x45800000, v25
	v_cndmask_b32_e32 v25, v25, v61, vcc
	v_mul_f32_e32 v61, v25, v98
	v_mul_f32_e32 v98, v25, v100
	v_mul_f32_e32 v100, v25, v102
	v_mul_f32_e32 v102, v25, v104
	v_mul_f32_e32 v99, v25, v99
	v_mul_f32_e32 v101, v25, v101
	v_fma_f32 v42, v42, v61, v66
	v_fma_f32 v43, v43, v98, v67
	v_fma_f32 v44, v44, v100, v68
	v_mul_f32_e32 v103, v25, v103
	v_mul_f32_e32 v104, v25, v105
	v_fmac_f32_e32 v69, v45, v102
	v_fma_f32 v45, v74, v99, v78
	v_fma_f32 v61, v75, v101, v79
	v_cvt_pk_bf16_f32 v42, v42, v43
	v_cvt_pk_bf16_f32 v43, v44, v69
	v_cvt_pk_bf16_f32 v44, v45, v61
	v_fma_f32 v66, v76, v103, v80
	v_fmac_f32_e32 v81, v104, v77
	v_cvt_pk_bf16_f32 v45, v66, v81
	global_store_dwordx2 v[94:95], v[42:43], off
	global_store_dwordx2 v[94:95], v[44:45], off offset:512
	v_add_f32_e32 v44, v46, v47
	ds_bpermute_b32 v45, v52, v44
	v_mul_f32_e32 v30, v25, v30
	v_mul_f32_e32 v105, v25, v106
	v_fma_f32 v30, v30, v82, v86
	v_fma_f32 v42, v105, v83, v87
	v_cvt_pk_bf16_f32 v42, v30, v42
	v_mul_f32_e32 v30, v25, v108
	v_fma_f32 v30, v30, v84, v88
	v_mul_f32_e32 v43, v25, v110
	v_fmac_f32_e32 v89, v43, v85
	v_cvt_pk_bf16_f32 v43, v30, v89
	s_waitcnt lgkmcnt(0)
	v_add_f32_e32 v30, v44, v45
	ds_bpermute_b32 v46, v53, v30
	global_store_dwordx2 v[94:95], v[42:43], off offset:1024
	ds_read_b128 v[42:45], v49 offset:7168
	ds_read_b128 v[66:69], v49 offset:3072
	v_mul_f32_e32 v31, v25, v31
	ds_read_b128 v[74:77], v49 offset:7168
	ds_read_b128 v[78:81], v49 offset:3072
	s_waitcnt lgkmcnt(4)
	v_add_f32_e32 v30, v30, v46
	ds_bpermute_b32 v46, v54, v30
	s_waitcnt lgkmcnt(3)
	v_fma_f32 v31, v31, v42, v66
	v_mul_f32_e32 v42, v25, v107
	v_fma_f32 v42, v42, v43, v67
	s_waitcnt lgkmcnt(0)
	v_add_f32_e32 v43, v30, v46
	ds_bpermute_b32 v46, v55, v43
	v_cvt_pk_bf16_f32 v30, v31, v42
	v_mul_f32_e32 v31, v25, v109
	v_mul_f32_e32 v25, v25, v111
	v_fmac_f32_e32 v69, v25, v45
	s_waitcnt lgkmcnt(0)
	v_add_f32_e32 v42, v43, v46
	v_fmamk_f32 v42, v42, 0x3a800000, v60
	v_mul_f32_e32 v43, 0x4b800000, v42
	v_cmp_gt_f32_e32 vcc, s34, v42
	v_fma_f32 v31, v31, v44, v68
	v_cvt_pk_bf16_f32 v31, v31, v69
	global_store_dwordx2 v[94:95], v[30:31], off offset:1536
	v_cndmask_b32_e32 v42, v42, v43, vcc
	v_rsq_f32_e32 v42, v42
	s_waitcnt vmcnt(6)
	v_and_b32_e32 v47, 0xffff0000, v92
	v_and_b32_e32 v46, 0xffff0000, v90
	v_lshlrev_b32_e32 v45, 16, v93
	v_mul_f32_e32 v25, 0x45800000, v42
	v_cndmask_b32_e32 v61, v42, v25, vcc
	v_mul_f32_e32 v25, v61, v112
	v_mul_f32_e32 v30, v61, v114
	v_fma_f32 v25, v62, v25, v70
	v_fma_f32 v30, v63, v30, v71
	v_cvt_pk_bf16_f32 v30, v25, v30
	v_mul_f32_e32 v25, v61, v116
	v_fma_f32 v25, v64, v25, v72
	v_mul_f32_e32 v31, v61, v40
	v_fmac_f32_e32 v73, v65, v31
	v_cvt_pk_bf16_f32 v31, v25, v73
	v_mul_f32_e32 v25, v61, v113
	v_fma_f32 v10, v10, v25, v14
	v_mul_f32_e32 v14, v61, v115
	v_fma_f32 v11, v11, v14, v15
	v_cvt_pk_bf16_f32 v40, v10, v11
	v_mul_f32_e32 v10, v61, v117
	v_lshl_add_u64 v[62:63], v[22:23], 0, v[28:29]
	v_fma_f32 v12, v12, v10, v16
	v_lshlrev_b32_e32 v65, 16, v92
	v_lshlrev_b32_e32 v64, 16, v90
	v_pk_mul_f32 v[10:11], v[46:47], v[46:47]
	s_waitcnt vmcnt(4)
	v_and_b32_e32 v29, 0xffff0000, v96
	v_and_b32_e32 v28, 0xffff0000, v118
	global_store_dwordx2 v[62:63], v[30:31], off
	v_lshlrev_b32_e32 v44, 16, v91
	v_pk_fma_f32 v[10:11], v[64:65], v[64:65], v[10:11]
	v_lshlrev_b32_e32 v31, 16, v96
	v_lshlrev_b32_e32 v30, 16, v118
	v_pk_mul_f32 v[68:69], v[28:29], v[28:29]
	v_and_b32_e32 v43, 0xffff0000, v93
	v_and_b32_e32 v42, 0xffff0000, v91
	v_pk_fma_f32 v[10:11], v[44:45], v[44:45], v[10:11]
	v_lshlrev_b32_e32 v15, 16, v97
	v_lshlrev_b32_e32 v14, 16, v119
	v_pk_fma_f32 v[68:69], v[30:31], v[30:31], v[68:69]
	v_pk_fma_f32 v[66:67], v[42:43], v[42:43], v[10:11]
	v_and_b32_e32 v11, 0xffff0000, v97
	v_and_b32_e32 v10, 0xffff0000, v119
	v_pk_fma_f32 v[68:69], v[14:15], v[14:15], v[68:69]
	v_add_f32_e32 v16, v66, v67
	v_pk_fma_f32 v[68:69], v[10:11], v[10:11], v[68:69]
	v_mul_f32_e32 v41, v61, v41
	v_add_f32_e32 v16, v16, v68
	v_add_f32_e32 v16, v16, v69
	ds_bpermute_b32 v68, v50, v16
	v_fmac_f32_e32 v17, v41, v13
	v_cvt_pk_bf16_f32 v41, v12, v17
	v_ashrrev_i32_e32 v25, 31, v24
	v_lshlrev_b64 v[24:25], 11, v[24:25]
	s_waitcnt lgkmcnt(0)
	v_add_f32_e32 v12, v16, v68
	ds_bpermute_b32 v13, v51, v12
	v_lshl_add_u64 v[66:67], v[20:21], 0, v[24:25]
	global_load_dwordx2 v[70:71], v[66:67], off
	global_load_dwordx2 v[72:73], v[66:67], off offset:512
	v_mul_f32_e32 v16, v61, v38
	global_store_dwordx2 v[62:63], v[40:41], off offset:512
	v_fma_f32 v2, v16, v2, v6
	v_mul_f32_e32 v6, v61, v36
	s_waitcnt lgkmcnt(0)
	v_add_f32_e32 v36, v12, v13
	global_load_dwordx2 v[12:13], v[66:67], off offset:1024
	global_load_dwordx2 v[16:17], v[66:67], off offset:1536
	ds_bpermute_b32 v38, v52, v36
	v_fma_f32 v3, v6, v3, v7
	v_cvt_pk_bf16_f32 v2, v2, v3
	v_mul_f32_e32 v3, v61, v34
	v_fma_f32 v3, v3, v4, v8
	s_waitcnt lgkmcnt(0)
	v_add_f32_e32 v4, v36, v38
	ds_bpermute_b32 v6, v53, v4
	v_mul_f32_e32 v7, v61, v32
	v_fmac_f32_e32 v9, v7, v5
	v_cvt_pk_bf16_f32 v3, v3, v9
	global_store_dwordx2 v[62:63], v[2:3], off offset:1024
	s_waitcnt lgkmcnt(0)
	v_add_f32_e32 v2, v4, v6
	ds_bpermute_b32 v3, v54, v2
	v_mul_f32_e32 v4, v61, v39
	v_mul_f32_e32 v5, v61, v37
	v_fma_f32 v4, v4, v74, v78
	v_fma_f32 v5, v5, v75, v79
	s_waitcnt lgkmcnt(0)
	v_add_f32_e32 v3, v2, v3
	ds_bpermute_b32 v6, v55, v3
	v_cvt_pk_bf16_f32 v2, v4, v5
	v_mul_f32_e32 v4, v61, v35
	v_mul_f32_e32 v5, v61, v33
	v_fma_f32 v4, v4, v76, v80
	s_waitcnt lgkmcnt(0)
	v_add_f32_e32 v3, v3, v6
	v_fmamk_f32 v3, v3, 0x3a800000, v60
	v_mul_f32_e32 v6, 0x4b800000, v3
	v_cmp_gt_f32_e32 vcc, s34, v3
	v_fmac_f32_e32 v81, v5, v77
	s_waitcnt vmcnt(5)
	v_and_b32_e32 v80, 0xffff0000, v70
	v_cndmask_b32_e32 v3, v3, v6, vcc
	v_rsq_f32_e32 v32, v3
	v_cvt_pk_bf16_f32 v3, v4, v81
	global_store_dwordx2 v[62:63], v[2:3], off offset:1536
	ds_read_b128 v[2:5], v49 offset:4096
	ds_read_b128 v[6:9], v49
	v_mul_f32_e32 v33, 0x45800000, v32
	v_cndmask_b32_e32 v61, v32, v33, vcc
	v_mul_f32_e32 v40, v61, v64
	ds_read_b128 v[32:35], v49 offset:4096
	ds_read_b128 v[36:39], v49
	s_waitcnt lgkmcnt(2)
	v_fma_f32 v2, v2, v40, v6
	v_mul_f32_e32 v6, v61, v46
	v_fma_f32 v3, v3, v6, v7
	v_cvt_pk_bf16_f32 v40, v2, v3
	v_mul_f32_e32 v2, v61, v44
	v_mul_f32_e32 v3, v61, v42
	v_fma_f32 v2, v4, v2, v8
	v_fmac_f32_e32 v9, v5, v3
	v_cvt_pk_bf16_f32 v41, v2, v9
	ds_read_b128 v[2:5], v49 offset:5120
	ds_read_b128 v[6:9], v49 offset:1024
	global_store_dwordx2 v[26:27], v[40:41], off
	v_mul_f32_e32 v40, v61, v65
	s_waitcnt vmcnt(6)
	v_and_b32_e32 v81, 0xffff0000, v72
	v_lshlrev_b32_e32 v79, 16, v72
	s_waitcnt lgkmcnt(0)
	v_fma_f32 v2, v2, v40, v6
	v_lshlrev_b32_e32 v78, 16, v70
	v_pk_mul_f32 v[40:41], v[80:81], v[80:81]
	s_waitcnt vmcnt(3)
	v_and_b32_e32 v89, 0xffff0000, v16
	v_and_b32_e32 v88, 0xffff0000, v12
	v_lshlrev_b32_e32 v83, 16, v73
	v_lshlrev_b32_e32 v82, 16, v71
	v_pk_fma_f32 v[40:41], v[78:79], v[78:79], v[40:41]
	v_lshlrev_b32_e32 v87, 16, v16
	v_lshlrev_b32_e32 v86, 16, v12
	v_lshlrev_b32_e32 v90, 16, v13
	v_and_b32_e32 v16, 0xffff0000, v13
	v_pk_mul_f32 v[12:13], v[88:89], v[88:89]
	v_mul_f32_e32 v6, v61, v47
	v_and_b32_e32 v85, 0xffff0000, v73
	v_and_b32_e32 v84, 0xffff0000, v71
	v_pk_fma_f32 v[40:41], v[82:83], v[82:83], v[40:41]
	v_lshlrev_b32_e32 v91, 16, v17
	v_pk_fma_f32 v[12:13], v[86:87], v[86:87], v[12:13]
	v_fma_f32 v3, v3, v6, v7
	v_pk_fma_f32 v[40:41], v[84:85], v[84:85], v[40:41]
	v_and_b32_e32 v17, 0xffff0000, v17
	v_pk_fma_f32 v[12:13], v[90:91], v[90:91], v[12:13]
	v_cvt_pk_bf16_f32 v2, v2, v3
	v_mul_f32_e32 v3, v61, v45
	v_pk_fma_f32 v[12:13], v[16:17], v[16:17], v[12:13]
	v_add_f32_e32 v40, v40, v41
	v_fma_f32 v3, v4, v3, v8
	v_mul_f32_e32 v4, v61, v43
	v_add_f32_e32 v12, v40, v12
	ds_read_b128 v[62:65], v49 offset:5120
	ds_read_b128 v[66:69], v49 offset:1024
	v_fmac_f32_e32 v9, v4, v5
	v_cvt_pk_bf16_f32 v3, v3, v9
	global_store_dwordx2 v[26:27], v[2:3], off offset:512
	v_add_f32_e32 v12, v12, v13
	ds_read_b128 v[2:5], v49 offset:6144
	ds_read_b128 v[6:9], v49 offset:2048
	ds_bpermute_b32 v13, v50, v12
	v_mul_f32_e32 v30, v61, v30
	ds_read_b128 v[40:43], v49 offset:6144
	ds_read_b128 v[44:47], v49 offset:2048
	s_waitcnt lgkmcnt(3)
	v_fma_f32 v2, v30, v2, v6
	s_waitcnt lgkmcnt(2)
	v_add_f32_e32 v6, v12, v13
	ds_bpermute_b32 v12, v51, v6
	v_mul_f32_e32 v13, v61, v28
	v_fma_f32 v3, v13, v3, v7
	v_cvt_pk_bf16_f32 v2, v2, v3
	v_mul_f32_e32 v3, v61, v14
	s_waitcnt lgkmcnt(0)
	v_add_f32_e32 v6, v6, v12
	ds_bpermute_b32 v7, v52, v6
	v_fma_f32 v3, v3, v4, v8
	v_mul_f32_e32 v4, v61, v10
	v_fmac_f32_e32 v9, v4, v5
	v_cvt_pk_bf16_f32 v3, v3, v9
	s_waitcnt lgkmcnt(0)
	v_add_f32_e32 v10, v6, v7
	ds_bpermute_b32 v12, v53, v10
	global_store_dwordx2 v[26:27], v[2:3], off offset:1024
	ds_read_b128 v[2:5], v49 offset:7168
	ds_read_b128 v[6:9], v49 offset:3072
	v_mul_f32_e32 v13, v61, v31
	ds_read_b128 v[70:73], v49 offset:7168
	ds_read_b128 v[74:77], v49 offset:3072
	s_waitcnt lgkmcnt(4)
	v_add_f32_e32 v10, v10, v12
	ds_bpermute_b32 v12, v54, v10
	s_waitcnt lgkmcnt(3)
	v_fma_f32 v2, v13, v2, v6
	v_mul_f32_e32 v6, v61, v29
	v_fma_f32 v3, v6, v3, v7
	v_cvt_pk_bf16_f32 v2, v2, v3
	s_waitcnt lgkmcnt(0)
	v_add_f32_e32 v6, v10, v12
	ds_bpermute_b32 v7, v55, v6
	v_mul_f32_e32 v3, v61, v15
	v_fma_f32 v3, v3, v4, v8
	v_mul_f32_e32 v4, v61, v11
	v_fmac_f32_e32 v9, v4, v5
	s_waitcnt lgkmcnt(0)
	v_add_f32_e32 v6, v6, v7
	v_fmamk_f32 v6, v6, 0x3a800000, v60
	v_mul_f32_e32 v7, 0x4b800000, v6
	v_cmp_gt_f32_e32 vcc, s34, v6
	v_cvt_pk_bf16_f32 v3, v3, v9
	global_store_dwordx2 v[26:27], v[2:3], off offset:1536
	s_nop 0
	v_cndmask_b32_e32 v6, v6, v7, vcc
	v_rsq_f32_e32 v6, v6
	s_nop 0
	v_mul_f32_e32 v2, 0x45800000, v6
	v_cndmask_b32_e32 v6, v6, v2, vcc
	v_mul_f32_e32 v2, v6, v78
	v_mul_f32_e32 v3, v6, v80
	v_fma_f32 v2, v32, v2, v36
	v_fma_f32 v3, v33, v3, v37
	v_cvt_pk_bf16_f32 v2, v2, v3
	v_mul_f32_e32 v3, v6, v82
	v_fma_f32 v3, v34, v3, v38
	v_mul_f32_e32 v4, v6, v84
	v_fmac_f32_e32 v39, v35, v4
	v_cvt_pk_bf16_f32 v3, v3, v39
	v_lshl_add_u64 v[4:5], v[22:23], 0, v[24:25]
	global_store_dwordx2 v[4:5], v[2:3], off
	v_mul_f32_e32 v2, v6, v79
	v_mul_f32_e32 v3, v6, v81
	v_fma_f32 v2, v62, v2, v66
	v_fma_f32 v3, v63, v3, v67
	v_cvt_pk_bf16_f32 v2, v2, v3
	v_mul_f32_e32 v3, v6, v83
	v_fma_f32 v3, v64, v3, v68
	v_mul_f32_e32 v7, v6, v85
	v_fmac_f32_e32 v69, v7, v65
	v_cvt_pk_bf16_f32 v3, v3, v69
	global_store_dwordx2 v[4:5], v[2:3], off offset:512
	v_mul_f32_e32 v2, v6, v86
	v_mul_f32_e32 v3, v6, v88
	v_fma_f32 v2, v2, v40, v44
	v_fma_f32 v3, v3, v41, v45
	v_cvt_pk_bf16_f32 v2, v2, v3
	v_mul_f32_e32 v3, v6, v90
	v_fma_f32 v3, v3, v42, v46
	v_mul_f32_e32 v7, v6, v16
	v_fmac_f32_e32 v47, v7, v43
	v_cvt_pk_bf16_f32 v3, v3, v47
	global_store_dwordx2 v[4:5], v[2:3], off offset:1024
	v_mul_f32_e32 v2, v6, v87
	v_mul_f32_e32 v3, v6, v89
	v_fma_f32 v2, v2, v70, v74
	v_fma_f32 v3, v3, v71, v75
	v_cvt_pk_bf16_f32 v2, v2, v3
	v_mul_f32_e32 v3, v6, v91
	v_fma_f32 v3, v3, v72, v76
	v_mul_f32_e32 v6, v6, v17
	v_fmac_f32_e32 v77, v6, v73
	v_cvt_pk_bf16_f32 v3, v3, v77
	global_store_dwordx2 v[4:5], v[2:3], off offset:1536
	s_barrier
	s_cbranch_scc1 .LBB0_850
.LBB0_835:
	s_lshl_b32 s36, s35, 5
	v_add_u32_e32 v200, s36, v1
	v_lshlrev_b32_e32 v200, 11, v200
	v_mov_b32_e32 v201, 0
	v_lshl_add_u64 v[200:201], v[200:201], 0, v[20:21]
	global_load_dwordx2 v[210:211], v[200:201], off offset:512
	global_load_dwordx2 v[212:213], v[200:201], off
	global_load_dwordx2 v[214:215], v[200:201], off offset:1536
	global_load_dwordx2 v[216:217], v[200:201], off offset:1024
	global_load_dwordx2 v[218:219], v[200:201], off offset:2560
	global_load_dwordx2 v[220:221], v[200:201], off offset:2048
	global_load_dwordx2 v[222:223], v[200:201], off offset:3584
	global_load_dwordx2 v[224:225], v[200:201], off offset:3072
	s_and_saveexec_b64 s[18:19], s[6:7]
	s_cbranch_execz .LBB0_834
	s_add_i32 s16, s36, 0xffffe000
	s_ashr_i32 s16, s16, 10
	s_cmpk_gt_i32 s35, 0xff
	s_cselect_b32 s38, s16, 8
	s_mul_hi_i32 s37, s38, 0x6000
	s_mulk_i32 s38, 0x6000
	s_mov_b64 s[16:17], -1
	v_mov_b32_e32 v6, v18
	v_mov_b32_e32 v8, v48
	s_and_saveexec_b64 s[20:21], s[8:9]
	s_cbranch_execz .LBB0_847
	s_add_u32 s22, s2, s38
	s_addc_u32 s23, s3, s37
	v_mov_b32_e32 v6, 0
	v_mov_b64_e32 v[2:3], v[18:19]
	s_and_saveexec_b64 s[24:25], s[10:11]
	s_cbranch_execz .LBB0_841
	s_mov_b32 s39, 0
	s_mov_b64 s[26:27], 0
	v_mov_b32_e32 v4, v58
	v_mov_b32_e32 v5, v59
	v_mov_b64_e32 v[2:3], v[18:19]

.LBB0_956:
	s_mul_hi_u32 s0, s67, 0x580
	s_mul_i32 s0, s0, s66
	s_sub_i32 s0, 0x580, s0
	s_sub_i32 s1, s0, s66
	s_cmp_ge_u32 s0, s66
	s_cselect_b32 s0, s1, s0
	s_sub_i32 s1, s0, s66
	s_cmp_ge_u32 s0, s66
	s_cselect_b32 s3, s1, s0
	s_cmp_lt_i32 s83, s3
	s_cbranch_scc1 .Ltail1_unitwg
	s_sub_i32 s2, s83, s3
	s_movk_i32 s98, 0x370
	s_sub_i32 s99, s84, s3
	s_branch .Ltail1_common
.Ltail1_unitwg:
	s_add_i32 s2, s83, 0x370
	s_movk_i32 s98, 0x6d0
	s_mov_b32 s99, s3

.LBB0_1191:
	s_or_b64 exec, exec, s[16:17]
	v_add_u32_e32 v24, s30, v1
	v_ashrrev_i32_e32 v25, 31, v24
	v_lshlrev_b64 v[26:27], 11, v[24:25]
	v_lshl_add_u64 v[2:3], v[20:21], 0, v[26:27]
	s_waitcnt lgkmcnt(0)
	s_barrier
	s_waitcnt vmcnt(0)
	v_mov_b64_e32 v[32:33], v[210:211]
	v_mov_b64_e32 v[30:31], v[212:213]
	v_mov_b64_e32 v[36:37], v[214:215]
	v_mov_b64_e32 v[34:35], v[216:217]
	v_or_b32_e32 v2, 1, v24
	v_ashrrev_i32_e32 v3, 31, v2
	v_lshlrev_b64 v[28:29], 11, v[2:3]
	v_lshl_add_u64 v[2:3], v[20:21], 0, v[28:29]
	v_mov_b64_e32 v[38:39], v[218:219]
	v_mov_b64_e32 v[46:47], v[220:221]
	v_mov_b64_e32 v[90:91], v[222:223]
	v_mov_b64_e32 v[92:93], v[224:225]
	v_or_b32_e32 v40, 2, v24
	v_ashrrev_i32_e32 v41, 31, v40
	v_lshl_add_u64 v[94:95], v[22:23], 0, v[26:27]
	v_lshlrev_b64 v[26:27], 11, v[40:41]
	v_lshl_add_u64 v[96:97], v[20:21], 0, v[26:27]
	ds_read_b128 v[42:45], v49 offset:4096
	ds_read_b128 v[62:65], v49 offset:4096
	ds_read_b128 v[66:69], v49
	ds_read_b128 v[70:73], v49
	ds_read_b128 v[74:77], v49 offset:5120
	ds_read_b128 v[10:13], v49 offset:5120
	ds_read_b128 v[78:81], v49 offset:1024
	ds_read_b128 v[14:17], v49 offset:1024
	ds_read_b128 v[82:85], v49 offset:6144
	ds_read_b128 v[2:5], v49 offset:6144
	ds_read_b128 v[86:89], v49 offset:2048
	ds_read_b128 v[6:9], v49 offset:2048
	v_or_b32_e32 v24, 3, v24
	v_lshl_add_u64 v[26:27], v[22:23], 0, v[26:27]
	s_add_i32 s29, s29, s84
	s_cmpk_gt_i32 s29, 0x1ff
	s_waitcnt vmcnt(7)
	v_and_b32_e32 v101, 0xffff0000, v32
	s_waitcnt vmcnt(6)
	v_and_b32_e32 v100, 0xffff0000, v30
	v_lshlrev_b32_e32 v99, 16, v32
	v_lshlrev_b32_e32 v98, 16, v30
	v_lshlrev_b32_e32 v103, 16, v33
	v_and_b32_e32 v105, 0xffff0000, v33
	s_waitcnt vmcnt(5)
	v_and_b32_e32 v107, 0xffff0000, v36
	s_waitcnt vmcnt(4)
	v_and_b32_e32 v106, 0xffff0000, v34
	v_pk_mul_f32 v[32:33], v[100:101], v[100:101]
	v_lshlrev_b32_e32 v102, 16, v31
	v_and_b32_e32 v104, 0xffff0000, v31
	v_lshlrev_b32_e32 v31, 16, v36
	v_lshlrev_b32_e32 v30, 16, v34
	v_lshlrev_b32_e32 v108, 16, v35
	v_and_b32_e32 v110, 0xffff0000, v35
	v_pk_mul_f32 v[34:35], v[106:107], v[106:107]
	v_pk_fma_f32 v[32:33], v[98:99], v[98:99], v[32:33]
	v_lshlrev_b32_e32 v109, 16, v37
	v_pk_fma_f32 v[34:35], v[30:31], v[30:31], v[34:35]
	v_pk_fma_f32 v[32:33], v[102:103], v[102:103], v[32:33]
	v_and_b32_e32 v111, 0xffff0000, v37
	v_pk_fma_f32 v[34:35], v[108:109], v[108:109], v[34:35]
	v_pk_fma_f32 v[32:33], v[104:105], v[104:105], v[32:33]
	v_pk_fma_f32 v[34:35], v[110:111], v[110:111], v[34:35]
	v_add_f32_e32 v25, v32, v33
	v_add_f32_e32 v25, v25, v34
	v_add_f32_e32 v25, v25, v35
	ds_bpermute_b32 v32, v50, v25
	s_waitcnt vmcnt(2)
	v_lshlrev_b32_e32 v112, 16, v46
	v_and_b32_e32 v114, 0xffff0000, v46
	v_and_b32_e32 v115, 0xffff0000, v38
	v_lshlrev_b32_e32 v113, 16, v38
	s_waitcnt lgkmcnt(0)
	v_add_f32_e32 v25, v25, v32
	ds_bpermute_b32 v32, v51, v25
	v_lshlrev_b32_e32 v116, 16, v47
	v_and_b32_e32 v40, 0xffff0000, v47
	s_waitcnt vmcnt(1)
	v_and_b32_e32 v37, 0xffff0000, v90
	s_waitcnt vmcnt(0)
	v_and_b32_e32 v36, 0xffff0000, v92
	s_waitcnt lgkmcnt(0)
	v_add_f32_e32 v25, v25, v32
	ds_bpermute_b32 v46, v52, v25
	v_lshlrev_b32_e32 v117, 16, v39
	v_and_b32_e32 v41, 0xffff0000, v39
	v_lshlrev_b32_e32 v39, 16, v90
	v_lshlrev_b32_e32 v38, 16, v92
	s_waitcnt lgkmcnt(0)
	v_add_f32_e32 v25, v25, v46
	v_pk_mul_f32 v[46:47], v[114:115], v[114:115]
	v_lshlrev_b32_e32 v35, 16, v91
	v_and_b32_e32 v33, 0xffff0000, v91
	v_pk_mul_f32 v[90:91], v[36:37], v[36:37]
	v_pk_fma_f32 v[46:47], v[112:113], v[112:113], v[46:47]
	v_lshlrev_b32_e32 v34, 16, v93
	v_pk_fma_f32 v[90:91], v[38:39], v[38:39], v[90:91]
	v_pk_fma_f32 v[46:47], v[116:117], v[116:117], v[46:47]
	v_and_b32_e32 v32, 0xffff0000, v93
	v_pk_fma_f32 v[90:91], v[34:35], v[34:35], v[90:91]
	v_pk_fma_f32 v[46:47], v[40:41], v[40:41], v[46:47]
	v_pk_fma_f32 v[90:91], v[32:33], v[32:33], v[90:91]
	v_add_f32_e32 v46, v46, v47
	v_add_f32_e32 v46, v46, v90
	v_add_f32_e32 v46, v46, v91
	global_load_dwordx2 v[90:91], v[96:97], off
	global_load_dwordx2 v[92:93], v[96:97], off offset:512
	global_load_dwordx2 v[118:119], v[96:97], off offset:1024
	s_nop 0
	global_load_dwordx2 v[96:97], v[96:97], off offset:1536
	ds_bpermute_b32 v61, v53, v25
	ds_bpermute_b32 v47, v50, v46
	s_waitcnt lgkmcnt(1)
	v_add_f32_e32 v25, v25, v61
	ds_bpermute_b32 v61, v54, v25
	s_waitcnt lgkmcnt(1)
	v_add_f32_e32 v46, v46, v47
	ds_bpermute_b32 v47, v51, v46
	s_waitcnt lgkmcnt(1)
	v_add_f32_e32 v25, v25, v61
	ds_bpermute_b32 v61, v55, v25
	s_waitcnt lgkmcnt(0)
	v_add_f32_e32 v25, v25, v61
	v_fmamk_f32 v25, v25, 0x3a800000, v60
	v_mul_f32_e32 v61, 0x4b800000, v25
	v_cmp_gt_f32_e32 vcc, s28, v25
	s_nop 1
	v_cndmask_b32_e32 v25, v25, v61, vcc
	v_rsq_f32_e32 v25, v25
	s_nop 0
	v_mul_f32_e32 v61, 0x45800000, v25
	v_cndmask_b32_e32 v25, v25, v61, vcc
	v_mul_f32_e32 v61, v25, v98
	v_mul_f32_e32 v98, v25, v100
	v_mul_f32_e32 v100, v25, v102
	v_mul_f32_e32 v102, v25, v104
	v_mul_f32_e32 v99, v25, v99
	v_mul_f32_e32 v101, v25, v101
	v_fma_f32 v42, v42, v61, v66
	v_fma_f32 v43, v43, v98, v67
	v_fma_f32 v44, v44, v100, v68
	v_mul_f32_e32 v103, v25, v103
	v_mul_f32_e32 v104, v25, v105
	v_fmac_f32_e32 v69, v45, v102
	v_fma_f32 v45, v74, v99, v78
	v_fma_f32 v61, v75, v101, v79
	v_cvt_pk_bf16_f32 v42, v42, v43
	v_cvt_pk_bf16_f32 v43, v44, v69
	v_cvt_pk_bf16_f32 v44, v45, v61
	v_fma_f32 v66, v76, v103, v80
	v_fmac_f32_e32 v81, v104, v77
	v_cvt_pk_bf16_f32 v45, v66, v81
	global_store_dwordx2 v[94:95], v[42:43], off
	global_store_dwordx2 v[94:95], v[44:45], off offset:512
	v_add_f32_e32 v44, v46, v47
	ds_bpermute_b32 v45, v52, v44
	v_mul_f32_e32 v30, v25, v30
	v_mul_f32_e32 v105, v25, v106
	v_fma_f32 v30, v30, v82, v86
	v_fma_f32 v42, v105, v83, v87
	v_cvt_pk_bf16_f32 v42, v30, v42
	v_mul_f32_e32 v30, v25, v108
	v_fma_f32 v30, v30, v84, v88
	v_mul_f32_e32 v43, v25, v110
	v_fmac_f32_e32 v89, v43, v85
	v_cvt_pk_bf16_f32 v43, v30, v89
	s_waitcnt lgkmcnt(0)
	v_add_f32_e32 v30, v44, v45
	ds_bpermute_b32 v46, v53, v30
	global_store_dwordx2 v[94:95], v[42:43], off offset:1024
	ds_read_b128 v[42:45], v49 offset:7168
	ds_read_b128 v[66:69], v49 offset:3072
	v_mul_f32_e32 v31, v25, v31
	ds_read_b128 v[74:77], v49 offset:7168
	ds_read_b128 v[78:81], v49 offset:3072
	s_waitcnt lgkmcnt(4)
	v_add_f32_e32 v30, v30, v46
	ds_bpermute_b32 v46, v54, v30
	s_waitcnt lgkmcnt(3)
	v_fma_f32 v31, v31, v42, v66
	v_mul_f32_e32 v42, v25, v107
	v_fma_f32 v42, v42, v43, v67
	s_waitcnt lgkmcnt(0)
	v_add_f32_e32 v43, v30, v46
	ds_bpermute_b32 v46, v55, v43
	v_cvt_pk_bf16_f32 v30, v31, v42
	v_mul_f32_e32 v31, v25, v109
	v_mul_f32_e32 v25, v25, v111
	v_fmac_f32_e32 v69, v25, v45
	s_waitcnt lgkmcnt(0)
	v_add_f32_e32 v42, v43, v46
	v_fmamk_f32 v42, v42, 0x3a800000, v60
	v_mul_f32_e32 v43, 0x4b800000, v42
	v_cmp_gt_f32_e32 vcc, s28, v42
	v_fma_f32 v31, v31, v44, v68
	v_cvt_pk_bf16_f32 v31, v31, v69
	global_store_dwordx2 v[94:95], v[30:31], off offset:1536
	v_cndmask_b32_e32 v42, v42, v43, vcc
	v_rsq_f32_e32 v42, v42
	s_waitcnt vmcnt(6)
	v_and_b32_e32 v47, 0xffff0000, v92
	v_and_b32_e32 v46, 0xffff0000, v90
	v_lshlrev_b32_e32 v45, 16, v93
	v_mul_f32_e32 v25, 0x45800000, v42
	v_cndmask_b32_e32 v61, v42, v25, vcc
	v_mul_f32_e32 v25, v61, v112
	v_mul_f32_e32 v30, v61, v114
	v_fma_f32 v25, v62, v25, v70
	v_fma_f32 v30, v63, v30, v71
	v_cvt_pk_bf16_f32 v30, v25, v30
	v_mul_f32_e32 v25, v61, v116
	v_fma_f32 v25, v64, v25, v72
	v_mul_f32_e32 v31, v61, v40
	v_fmac_f32_e32 v73, v65, v31
	v_cvt_pk_bf16_f32 v31, v25, v73
	v_mul_f32_e32 v25, v61, v113
	v_fma_f32 v10, v10, v25, v14
	v_mul_f32_e32 v14, v61, v115
	v_fma_f32 v11, v11, v14, v15
	v_cvt_pk_bf16_f32 v40, v10, v11
	v_mul_f32_e32 v10, v61, v117
	v_lshl_add_u64 v[62:63], v[22:23], 0, v[28:29]
	v_fma_f32 v12, v12, v10, v16
	v_lshlrev_b32_e32 v65, 16, v92
	v_lshlrev_b32_e32 v64, 16, v90
	v_pk_mul_f32 v[10:11], v[46:47], v[46:47]
	s_waitcnt vmcnt(4)
	v_and_b32_e32 v29, 0xffff0000, v96
	v_and_b32_e32 v28, 0xffff0000, v118
	global_store_dwordx2 v[62:63], v[30:31], off
	v_lshlrev_b32_e32 v44, 16, v91
	v_pk_fma_f32 v[10:11], v[64:65], v[64:65], v[10:11]
	v_lshlrev_b32_e32 v31, 16, v96
	v_lshlrev_b32_e32 v30, 16, v118
	v_pk_mul_f32 v[68:69], v[28:29], v[28:29]
	v_and_b32_e32 v43, 0xffff0000, v93
	v_and_b32_e32 v42, 0xffff0000, v91
	v_pk_fma_f32 v[10:11], v[44:45], v[44:45], v[10:11]
	v_lshlrev_b32_e32 v15, 16, v97
	v_lshlrev_b32_e32 v14, 16, v119
	v_pk_fma_f32 v[68:69], v[30:31], v[30:31], v[68:69]
	v_pk_fma_f32 v[66:67], v[42:43], v[42:43], v[10:11]
	v_and_b32_e32 v11, 0xffff0000, v97
	v_and_b32_e32 v10, 0xffff0000, v119
	v_pk_fma_f32 v[68:69], v[14:15], v[14:15], v[68:69]
	v_add_f32_e32 v16, v66, v67
	v_pk_fma_f32 v[68:69], v[10:11], v[10:11], v[68:69]
	v_mul_f32_e32 v41, v61, v41
	v_add_f32_e32 v16, v16, v68
	v_add_f32_e32 v16, v16, v69
	ds_bpermute_b32 v68, v50, v16
	v_fmac_f32_e32 v17, v41, v13
	v_cvt_pk_bf16_f32 v41, v12, v17
	v_ashrrev_i32_e32 v25, 31, v24
	v_lshlrev_b64 v[24:25], 11, v[24:25]
	s_waitcnt lgkmcnt(0)
	v_add_f32_e32 v12, v16, v68
	ds_bpermute_b32 v13, v51, v12
	v_lshl_add_u64 v[66:67], v[20:21], 0, v[24:25]
	global_load_dwordx2 v[70:71], v[66:67], off
	global_load_dwordx2 v[72:73], v[66:67], off offset:512
	v_mul_f32_e32 v16, v61, v38
	global_store_dwordx2 v[62:63], v[40:41], off offset:512
	v_fma_f32 v2, v16, v2, v6
	v_mul_f32_e32 v6, v61, v36
	s_waitcnt lgkmcnt(0)
	v_add_f32_e32 v36, v12, v13
	global_load_dwordx2 v[12:13], v[66:67], off offset:1024
	global_load_dwordx2 v[16:17], v[66:67], off offset:1536
	ds_bpermute_b32 v38, v52, v36
	v_fma_f32 v3, v6, v3, v7
	v_cvt_pk_bf16_f32 v2, v2, v3
	v_mul_f32_e32 v3, v61, v34
	v_fma_f32 v3, v3, v4, v8
	s_waitcnt lgkmcnt(0)
	v_add_f32_e32 v4, v36, v38
	ds_bpermute_b32 v6, v53, v4
	v_mul_f32_e32 v7, v61, v32
	v_fmac_f32_e32 v9, v7, v5
	v_cvt_pk_bf16_f32 v3, v3, v9
	global_store_dwordx2 v[62:63], v[2:3], off offset:1024
	s_waitcnt lgkmcnt(0)
	v_add_f32_e32 v2, v4, v6
	ds_bpermute_b32 v3, v54, v2
	v_mul_f32_e32 v4, v61, v39
	v_mul_f32_e32 v5, v61, v37
	v_fma_f32 v4, v4, v74, v78
	v_fma_f32 v5, v5, v75, v79
	s_waitcnt lgkmcnt(0)
	v_add_f32_e32 v3, v2, v3
	ds_bpermute_b32 v6, v55, v3
	v_cvt_pk_bf16_f32 v2, v4, v5
	v_mul_f32_e32 v4, v61, v35
	v_mul_f32_e32 v5, v61, v33
	v_fma_f32 v4, v4, v76, v80
	s_waitcnt lgkmcnt(0)
	v_add_f32_e32 v3, v3, v6
	v_fmamk_f32 v3, v3, 0x3a800000, v60
	v_mul_f32_e32 v6, 0x4b800000, v3
	v_cmp_gt_f32_e32 vcc, s28, v3
	v_fmac_f32_e32 v81, v5, v77
	s_waitcnt vmcnt(5)
	v_and_b32_e32 v80, 0xffff0000, v70
	v_cndmask_b32_e32 v3, v3, v6, vcc
	v_rsq_f32_e32 v32, v3
	v_cvt_pk_bf16_f32 v3, v4, v81
	global_store_dwordx2 v[62:63], v[2:3], off offset:1536
	ds_read_b128 v[2:5], v49 offset:4096
	ds_read_b128 v[6:9], v49
	v_mul_f32_e32 v33, 0x45800000, v32
	v_cndmask_b32_e32 v61, v32, v33, vcc
	v_mul_f32_e32 v40, v61, v64
	ds_read_b128 v[32:35], v49 offset:4096
	ds_read_b128 v[36:39], v49
	s_waitcnt lgkmcnt(2)
	v_fma_f32 v2, v2, v40, v6
	v_mul_f32_e32 v6, v61, v46
	v_fma_f32 v3, v3, v6, v7
	v_cvt_pk_bf16_f32 v40, v2, v3
	v_mul_f32_e32 v2, v61, v44
	v_mul_f32_e32 v3, v61, v42
	v_fma_f32 v2, v4, v2, v8
	v_fmac_f32_e32 v9, v5, v3
	v_cvt_pk_bf16_f32 v41, v2, v9
	ds_read_b128 v[2:5], v49 offset:5120
	ds_read_b128 v[6:9], v49 offset:1024
	global_store_dwordx2 v[26:27], v[40:41], off
	v_mul_f32_e32 v40, v61, v65
	s_waitcnt vmcnt(6)
	v_and_b32_e32 v81, 0xffff0000, v72
	v_lshlrev_b32_e32 v79, 16, v72
	s_waitcnt lgkmcnt(0)
	v_fma_f32 v2, v2, v40, v6
	v_lshlrev_b32_e32 v78, 16, v70
	v_pk_mul_f32 v[40:41], v[80:81], v[80:81]
	s_waitcnt vmcnt(3)
	v_and_b32_e32 v89, 0xffff0000, v16
	v_and_b32_e32 v88, 0xffff0000, v12
	v_lshlrev_b32_e32 v83, 16, v73
	v_lshlrev_b32_e32 v82, 16, v71
	v_pk_fma_f32 v[40:41], v[78:79], v[78:79], v[40:41]
	v_lshlrev_b32_e32 v87, 16, v16
	v_lshlrev_b32_e32 v86, 16, v12
	v_lshlrev_b32_e32 v90, 16, v13
	v_and_b32_e32 v16, 0xffff0000, v13
	v_pk_mul_f32 v[12:13], v[88:89], v[88:89]
	v_mul_f32_e32 v6, v61, v47
	v_and_b32_e32 v85, 0xffff0000, v73
	v_and_b32_e32 v84, 0xffff0000, v71
	v_pk_fma_f32 v[40:41], v[82:83], v[82:83], v[40:41]
	v_lshlrev_b32_e32 v91, 16, v17
	v_pk_fma_f32 v[12:13], v[86:87], v[86:87], v[12:13]
	v_fma_f32 v3, v3, v6, v7
	v_pk_fma_f32 v[40:41], v[84:85], v[84:85], v[40:41]
	v_and_b32_e32 v17, 0xffff0000, v17
	v_pk_fma_f32 v[12:13], v[90:91], v[90:91], v[12:13]
	v_cvt_pk_bf16_f32 v2, v2, v3
	v_mul_f32_e32 v3, v61, v45
	v_pk_fma_f32 v[12:13], v[16:17], v[16:17], v[12:13]
	v_add_f32_e32 v40, v40, v41
	v_fma_f32 v3, v4, v3, v8
	v_mul_f32_e32 v4, v61, v43
	v_add_f32_e32 v12, v40, v12
	ds_read_b128 v[62:65], v49 offset:5120
	ds_read_b128 v[66:69], v49 offset:1024
	v_fmac_f32_e32 v9, v4, v5
	v_cvt_pk_bf16_f32 v3, v3, v9
	global_store_dwordx2 v[26:27], v[2:3], off offset:512
	v_add_f32_e32 v12, v12, v13
	ds_read_b128 v[2:5], v49 offset:6144
	ds_read_b128 v[6:9], v49 offset:2048
	ds_bpermute_b32 v13, v50, v12
	v_mul_f32_e32 v30, v61, v30
	ds_read_b128 v[40:43], v49 offset:6144
	ds_read_b128 v[44:47], v49 offset:2048
	s_waitcnt lgkmcnt(3)
	v_fma_f32 v2, v30, v2, v6
	s_waitcnt lgkmcnt(2)
	v_add_f32_e32 v6, v12, v13
	ds_bpermute_b32 v12, v51, v6
	v_mul_f32_e32 v13, v61, v28
	v_fma_f32 v3, v13, v3, v7
	v_cvt_pk_bf16_f32 v2, v2, v3
	v_mul_f32_e32 v3, v61, v14
	s_waitcnt lgkmcnt(0)
	v_add_f32_e32 v6, v6, v12
	ds_bpermute_b32 v7, v52, v6
	v_fma_f32 v3, v3, v4, v8
	v_mul_f32_e32 v4, v61, v10
	v_fmac_f32_e32 v9, v4, v5
	v_cvt_pk_bf16_f32 v3, v3, v9
	s_waitcnt lgkmcnt(0)
	v_add_f32_e32 v10, v6, v7
	ds_bpermute_b32 v12, v53, v10
	global_store_dwordx2 v[26:27], v[2:3], off offset:1024
	ds_read_b128 v[2:5], v49 offset:7168
	ds_read_b128 v[6:9], v49 offset:3072
	v_mul_f32_e32 v13, v61, v31
	ds_read_b128 v[70:73], v49 offset:7168
	ds_read_b128 v[74:77], v49 offset:3072
	s_waitcnt lgkmcnt(4)
	v_add_f32_e32 v10, v10, v12
	ds_bpermute_b32 v12, v54, v10
	s_waitcnt lgkmcnt(3)
	v_fma_f32 v2, v13, v2, v6
	v_mul_f32_e32 v6, v61, v29
	v_fma_f32 v3, v6, v3, v7
	v_cvt_pk_bf16_f32 v2, v2, v3
	s_waitcnt lgkmcnt(0)
	v_add_f32_e32 v6, v10, v12
	ds_bpermute_b32 v7, v55, v6
	v_mul_f32_e32 v3, v61, v15
	v_fma_f32 v3, v3, v4, v8
	v_mul_f32_e32 v4, v61, v11
	v_fmac_f32_e32 v9, v4, v5
	s_waitcnt lgkmcnt(0)
	v_add_f32_e32 v6, v6, v7
	v_fmamk_f32 v6, v6, 0x3a800000, v60
	v_mul_f32_e32 v7, 0x4b800000, v6
	v_cmp_gt_f32_e32 vcc, s28, v6
	v_cvt_pk_bf16_f32 v3, v3, v9
	global_store_dwordx2 v[26:27], v[2:3], off offset:1536
	s_nop 0
	v_cndmask_b32_e32 v6, v6, v7, vcc
	v_rsq_f32_e32 v6, v6
	s_nop 0
	v_mul_f32_e32 v2, 0x45800000, v6
	v_cndmask_b32_e32 v6, v6, v2, vcc
	v_mul_f32_e32 v2, v6, v78
	v_mul_f32_e32 v3, v6, v80
	v_fma_f32 v2, v32, v2, v36
	v_fma_f32 v3, v33, v3, v37
	v_cvt_pk_bf16_f32 v2, v2, v3
	v_mul_f32_e32 v3, v6, v82
	v_fma_f32 v3, v34, v3, v38
	v_mul_f32_e32 v4, v6, v84
	v_fmac_f32_e32 v39, v35, v4
	v_cvt_pk_bf16_f32 v3, v3, v39
	v_lshl_add_u64 v[4:5], v[22:23], 0, v[24:25]
	global_store_dwordx2 v[4:5], v[2:3], off
	v_mul_f32_e32 v2, v6, v79
	v_mul_f32_e32 v3, v6, v81
	v_fma_f32 v2, v62, v2, v66
	v_fma_f32 v3, v63, v3, v67
	v_cvt_pk_bf16_f32 v2, v2, v3
	v_mul_f32_e32 v3, v6, v83
	v_fma_f32 v3, v64, v3, v68
	v_mul_f32_e32 v7, v6, v85
	v_fmac_f32_e32 v69, v7, v65
	v_cvt_pk_bf16_f32 v3, v3, v69
	global_store_dwordx2 v[4:5], v[2:3], off offset:512
	v_mul_f32_e32 v2, v6, v86
	v_mul_f32_e32 v3, v6, v88
	v_fma_f32 v2, v2, v40, v44
	v_fma_f32 v3, v3, v41, v45
	v_cvt_pk_bf16_f32 v2, v2, v3
	v_mul_f32_e32 v3, v6, v90
	v_fma_f32 v3, v3, v42, v46
	v_mul_f32_e32 v7, v6, v16
	v_fmac_f32_e32 v47, v7, v43
	v_cvt_pk_bf16_f32 v3, v3, v47
	global_store_dwordx2 v[4:5], v[2:3], off offset:1024
	v_mul_f32_e32 v2, v6, v87
	v_mul_f32_e32 v3, v6, v89
	v_fma_f32 v2, v2, v70, v74
	v_fma_f32 v3, v3, v71, v75
	v_cvt_pk_bf16_f32 v2, v2, v3
	v_mul_f32_e32 v3, v6, v91
	v_fma_f32 v3, v3, v72, v76
	v_mul_f32_e32 v6, v6, v17
	v_fmac_f32_e32 v77, v6, v73
	v_cvt_pk_bf16_f32 v3, v3, v77
	global_store_dwordx2 v[4:5], v[2:3], off offset:1536
	s_barrier
	s_cbranch_scc1 .LBB0_1207
.LBB0_1192:
	s_lshl_b32 s30, s29, 5
	v_add_u32_e32 v200, s30, v1
	v_lshlrev_b32_e32 v200, 11, v200
	v_mov_b32_e32 v201, 0
	v_lshl_add_u64 v[200:201], v[200:201], 0, v[20:21]
	global_load_dwordx2 v[210:211], v[200:201], off offset:512
	global_load_dwordx2 v[212:213], v[200:201], off
	global_load_dwordx2 v[214:215], v[200:201], off offset:1536
	global_load_dwordx2 v[216:217], v[200:201], off offset:1024
	global_load_dwordx2 v[218:219], v[200:201], off offset:2560
	global_load_dwordx2 v[220:221], v[200:201], off offset:2048
	global_load_dwordx2 v[222:223], v[200:201], off offset:3584
	global_load_dwordx2 v[224:225], v[200:201], off offset:3072
	s_and_saveexec_b64 s[16:17], s[6:7]
	s_cbranch_execz .LBB0_1191
	s_add_i32 s18, s30, 0xffffe000
	s_ashr_i32 s18, s18, 10
	s_add_i32 s18, s18, 9
	s_cmpk_gt_i32 s29, 0xff
	s_cselect_b32 s33, s18, 17
	s_mul_hi_i32 s31, s33, 0x6000
	s_mulk_i32 s33, 0x6000
	s_mov_b64 s[20:21], -1
	v_mov_b32_e32 v6, v18
	v_mov_b32_e32 v8, v48
	s_and_saveexec_b64 s[18:19], s[8:9]
	s_cbranch_execz .LBB0_1204
	s_add_u32 s20, s2, s33
	s_addc_u32 s21, s3, s31
	v_mov_b32_e32 v6, 0
	v_mov_b64_e32 v[2:3], v[18:19]
	s_and_saveexec_b64 s[22:23], s[10:11]
	s_cbranch_execz .LBB0_1198
	s_mov_b32 s34, 0
	s_mov_b64 s[24:25], 0
	v_mov_b32_e32 v4, v58
	v_mov_b32_e32 v5, v59
	v_mov_b64_e32 v[2:3], v[18:19]

.LBB0_1709:
	s_lshl_b32 s36, s35, 5
	v_add_u32_e32 v200, s36, v1
	v_lshlrev_b32_e32 v200, 11, v200
	v_mov_b32_e32 v201, 0
	v_lshl_add_u64 v[200:201], v[200:201], 0, v[20:21]
	global_load_dwordx2 v[210:211], v[200:201], off offset:512
	global_load_dwordx2 v[212:213], v[200:201], off
	global_load_dwordx2 v[214:215], v[200:201], off offset:1536
	global_load_dwordx2 v[216:217], v[200:201], off offset:1024
	global_load_dwordx2 v[218:219], v[200:201], off offset:2560
	global_load_dwordx2 v[220:221], v[200:201], off offset:2048
	global_load_dwordx2 v[222:223], v[200:201], off offset:3584
	global_load_dwordx2 v[224:225], v[200:201], off offset:3072
	s_and_saveexec_b64 s[18:19], s[4:5]
	s_cbranch_execz .LBB0_1708
	s_add_i32 s14, s36, 0xffffe000
	s_ashr_i32 s14, s14, 10
	s_add_i32 s14, s14, 9
	s_cmpk_gt_i32 s35, 0xff
	s_cselect_b32 s38, s14, 17
	s_mul_hi_i32 s37, s38, 0x6000
	s_mulk_i32 s38, 0x6000
	s_mov_b64 s[14:15], -1
	v_mov_b32_e32 v6, v18
	v_mov_b32_e32 v8, v48
	s_and_saveexec_b64 s[20:21], s[6:7]
	s_cbranch_execz .LBB0_1721
	s_add_u32 s22, s2, s38
	s_addc_u32 s23, s3, s37
	v_mov_b32_e32 v6, 0
	v_mov_b64_e32 v[2:3], v[18:19]
	s_and_saveexec_b64 s[24:25], s[8:9]
	s_cbranch_execz .LBB0_1715
	s_mov_b32 s39, 0
	s_mov_b64 s[26:27], 0
	v_mov_b32_e32 v4, v58
	v_mov_b32_e32 v5, v59
	v_mov_b64_e32 v[2:3], v[18:19]
